# G2 K-loop: loop-exit and mid-K tests moved in front of the closing barrier (back-edge rotation, as v23 did for G1/G3)
# speedup vs baseline: 1.0025x; 1.0025x over previous
; #define PG8_BAR __builtin_amdgcn_s_barrier()
; template <class Epi, class Sched, bool ALIGN_EPI = false, bool SP2 = false>
; __device__ __forceinline__ void gemm_phase(PG8_LAS unsigned char* lds, const Gemm g, const Sched& S, const Epi& E) {
;     ...
;     f32x4 acc[2][2][4][2];
; #pragma unroll
;     for (int a = 0; a < 2; ++a)
; #pragma unroll
;         for (int b = 0; b < 2; ++b)
; #pragma unroll
;             for (int m = 0; m < 4; ++m)
; #pragma unroll
;                 for (int n = 0; n < 2; ++n) acc[a][b][m][n] = (f32x4){0.f, 0.f, 0.f, 0.f};
;     bf16x8 At[4][2], B0[2][2], B1[2][2];
;     const char* cA = (const char*)g.A + (size_t)cur.pm * tstep; const char* cB = (const char*)g.Bt + (size_t)cur.pn * tstep;
;     S.a_ready(cur);
;     if constexpr (SP2) {
;         PG8_STAGE(PG8_SB(0, 0), cB, voffB); PG8_STAGE(PG8_SB(0, 1), cB + hstep, voffB); PG8_STAGE(PG8_SA(0, 0), cA, voffA); PG8_STAGE(PG8_SA(0, 1), cA + hstep, voffA);
;         if (wr == 1) PG8_BAR;
;         PG8_WAIT_V(2); PG8_BAR;
;         PG8_STAGE(PG8_SB(1, 0), cB + kstep, voffB); PG8_STAGE(PG8_SA(1, 0), cA + kstep, voffA); PG8_STAGE(PG8_SB(1, 1), cB + hstep + kstep, voffB);
;         PG8_WAIT_V(6); PG8_BAR;
;     } else {
;         PG8_STAGE(PG8_SB(0, 0), cB, voffB); PG8_STAGE(PG8_SA(0, 0), cA, voffA); PG8_STAGE(PG8_SB(0, 1), cB + hstep, voffB); PG8_STAGE(PG8_SA(0, 1), cA + hstep, voffA);
;         if (wr == 1) PG8_BAR;
;         PG8_WAIT_V(4); PG8_BAR;
;         PG8_STAGE(PG8_SB(1, 0), cB + kstep, voffB); PG8_STAGE(PG8_SA(1, 0), cA + kstep, voffA); PG8_STAGE(PG8_SB(1, 1), cB + hstep + kstep, voffB);
;         PG8_WAIT_V(6); PG8_BAR;
;     }
;     for (;;) {
;         const bool has_next = S.next(ui + 1, nxt);
;         const char* nA = has_next ? (const char*)g.A + (size_t)nxt.pm * tstep : cA; const char* nB = has_next ? (const char*)g.Bt + (size_t)nxt.pn * tstep : cB;
;         for (int t = 0; t < nt; t += 2) {
;             const bool last = (t == nt - 2);
;             const char* a1 = cA + (size_t)(t + 1) * kstep;
;             const char* a2 = last ? nA : cA + (size_t)(t + 2) * kstep; const char* b2 = last ? nB : cB + (size_t)(t + 2) * kstep;
;             const char* a3 = a2 + kstep; const char* b3 = b2 + kstep;
;             if (last && has_next) S.a_ready(nxt);
;             if constexpr (Epi::MID) { if (t == nt / 2) E.mid(acc, cur, wr, wc, fr, fq); }
;             if constexpr (SP2) {
.LBB0_76:
	s_ashr_i32 s53, s52, 31
	s_lshl_b64 s[2:3], s[52:53], 20
	s_add_u32 s54, s46, s2
	s_addc_u32 s55, s47, s3
	s_and_b64 s[2:3], s[38:39], exec
	s_cselect_b32 s2, s55, s59
	s_cselect_b32 s3, s54, s58
	s_ashr_i32 s51, s50, 31
	s_lshl_b64 s[56:57], s[50:51], 20
	s_add_u32 s56, s66, s56
	s_addc_u32 s57, s67, s57
	s_and_b64 s[64:65], s[38:39], exec
	s_cselect_b32 s51, s57, s61
	s_cselect_b32 s53, s56, s60
	s_add_u32 s76, s60, 0x100
	s_addc_u32 s77, s61, 0
	s_add_u32 s60, s58, 0x80080
	s_addc_u32 s61, s59, 0
	v_mov_b32_e32 v2, 0
	v_lshl_add_u32 v160, s63, 8, v138
	v_lshl_or_b32 v162, s62, 8, v183
	v_lshl_add_u64 v[164:165], s[60:61], 0, v[156:157]
	v_lshl_add_u64 v[166:167], s[60:61], 0, v[158:159]
	s_mov_b32 s78, -2
	s_mov_b64 s[60:61], 0
	v_mov_b32_e32 v3, v2
	v_mov_b32_e32 v4, v2
	v_mov_b32_e32 v5, v2
	v_mov_b32_e32 v6, v2
	v_mov_b32_e32 v7, v2
	v_mov_b32_e32 v8, v2
	v_mov_b32_e32 v9, v2
	v_mov_b32_e32 v18, v2
	v_mov_b32_e32 v19, v2
	v_mov_b32_e32 v20, v2
	v_mov_b32_e32 v21, v2
	v_mov_b32_e32 v22, v2
	v_mov_b32_e32 v23, v2
	v_mov_b32_e32 v24, v2
	v_mov_b32_e32 v25, v2
	v_mov_b32_e32 v34, v2
	v_mov_b32_e32 v35, v2
	v_mov_b32_e32 v36, v2
	v_mov_b32_e32 v37, v2
	v_mov_b32_e32 v38, v2
	v_mov_b32_e32 v39, v2
	v_mov_b32_e32 v40, v2
	v_mov_b32_e32 v41, v2
	v_mov_b32_e32 v50, v2
	v_mov_b32_e32 v51, v2
	v_mov_b32_e32 v52, v2
	v_mov_b32_e32 v53, v2
	v_mov_b32_e32 v54, v2
	v_mov_b32_e32 v55, v2
	v_mov_b32_e32 v56, v2
	v_mov_b32_e32 v57, v2
	v_mov_b32_e32 v10, v2
	v_mov_b32_e32 v11, v2
	v_mov_b32_e32 v12, v2
	v_mov_b32_e32 v13, v2
	v_mov_b32_e32 v14, v2
	v_mov_b32_e32 v15, v2
	v_mov_b32_e32 v16, v2
	v_mov_b32_e32 v17, v2
	v_mov_b32_e32 v26, v2
	v_mov_b32_e32 v27, v2
	v_mov_b32_e32 v28, v2
	v_mov_b32_e32 v29, v2
	v_mov_b32_e32 v30, v2
	v_mov_b32_e32 v31, v2
	v_mov_b32_e32 v32, v2
	v_mov_b32_e32 v33, v2
	v_mov_b32_e32 v42, v2
	v_mov_b32_e32 v43, v2
	v_mov_b32_e32 v44, v2
	v_mov_b32_e32 v45, v2
	v_mov_b32_e32 v46, v2
	v_mov_b32_e32 v47, v2
	v_mov_b32_e32 v48, v2
	v_mov_b32_e32 v49, v2
	v_mov_b32_e32 v58, v2
	v_mov_b32_e32 v59, v2
	v_mov_b32_e32 v60, v2
	v_mov_b32_e32 v61, v2
	v_mov_b32_e32 v62, v2
	v_mov_b32_e32 v63, v2
	v_mov_b32_e32 v64, v2
	v_mov_b32_e32 v65, v2
	v_mov_b32_e32 v66, v2
	v_mov_b32_e32 v67, v2
	v_mov_b32_e32 v68, v2
	v_mov_b32_e32 v69, v2
	v_mov_b32_e32 v70, v2
	v_mov_b32_e32 v71, v2
	v_mov_b32_e32 v72, v2
	v_mov_b32_e32 v73, v2
	v_mov_b32_e32 v82, v2
	v_mov_b32_e32 v83, v2
	v_mov_b32_e32 v84, v2
	v_mov_b32_e32 v85, v2
	v_mov_b32_e32 v86, v2
	v_mov_b32_e32 v87, v2
	v_mov_b32_e32 v88, v2
	v_mov_b32_e32 v89, v2
	v_mov_b32_e32 v98, v2
	v_mov_b32_e32 v99, v2
	v_mov_b32_e32 v100, v2
	v_mov_b32_e32 v101, v2
	v_mov_b32_e32 v102, v2
	v_mov_b32_e32 v103, v2
	v_mov_b32_e32 v104, v2
	v_mov_b32_e32 v105, v2
	v_mov_b32_e32 v114, v2
	v_mov_b32_e32 v115, v2
	v_mov_b32_e32 v116, v2
	v_mov_b32_e32 v117, v2
	v_mov_b32_e32 v118, v2
	v_mov_b32_e32 v119, v2
	v_mov_b32_e32 v120, v2
	v_mov_b32_e32 v121, v2
	v_mov_b32_e32 v74, v2
	v_mov_b32_e32 v75, v2
	v_mov_b32_e32 v76, v2
	v_mov_b32_e32 v77, v2
	v_mov_b32_e32 v78, v2
	v_mov_b32_e32 v79, v2
	v_mov_b32_e32 v80, v2
	v_mov_b32_e32 v81, v2
	v_mov_b32_e32 v90, v2
	v_mov_b32_e32 v91, v2
	v_mov_b32_e32 v92, v2
	v_mov_b32_e32 v93, v2
	v_mov_b32_e32 v94, v2
	v_mov_b32_e32 v95, v2
	v_mov_b32_e32 v96, v2
	v_mov_b32_e32 v97, v2
	v_mov_b32_e32 v106, v2
	v_mov_b32_e32 v107, v2
	v_mov_b32_e32 v108, v2
	v_mov_b32_e32 v109, v2
	v_mov_b32_e32 v110, v2
	v_mov_b32_e32 v111, v2
	v_mov_b32_e32 v112, v2
	v_mov_b32_e32 v113, v2
	v_mov_b32_e32 v122, v2
	v_mov_b32_e32 v123, v2
	v_mov_b32_e32 v124, v2
	v_mov_b32_e32 v125, v2
	v_mov_b32_e32 v126, v2
	v_mov_b32_e32 v127, v2
	v_mov_b32_e32 v128, v2
	v_mov_b32_e32 v129, v2
	s_branch .LBB0_78
.Lg2_head_bar:
	s_barrier
.LBB0_77:
	s_add_u32 s62, s58, s60
	s_addc_u32 s63, s59, s61
	s_add_u32 s62, s62, 0x100
	s_addc_u32 s63, s63, 0
	s_add_u32 s79, s76, s60
	s_addc_u32 s82, s77, s61
	s_cmpk_eq_i32 s60, 0xf00
	s_cselect_b32 s65, s2, s63
	s_cselect_b32 s64, s3, s62
	s_cselect_b32 s63, s51, s82
	s_cselect_b32 s62, s53, s79
	s_add_i32 s79, 0, 0x10000
	v_add_u32_e32 v142, s79, v182
	s_add_i32 s86, 0, 0x14000
	ds_read_b128 v[130:133], v142
	ds_read_b128 v[134:137], v142 offset:1024
	ds_read_b128 v[186:189], v142 offset:2048
	ds_read_b128 v[190:193], v142 offset:3072
	v_add_u32_e32 v142, s86, v182
	ds_read_b128 v[194:197], v142
	ds_read_b128 v[198:201], v142 offset:1024
	ds_read_b128 v[202:205], v142 offset:2048
	ds_read_b128 v[206:209], v142 offset:3072
	v_lshl_add_u64 v[168:169], v[166:167], 0, s[60:61]
	s_add_i32 m0, s69, 0xc000
	ds_read_b128 v[214:217], v184
	ds_read_b128 v[218:221], v184 offset:1024
	ds_read_b128 v[222:225], v184 offset:2048
	ds_read_b128 v[226:229], v184 offset:3072
	ds_read_b128 v[230:233], v184 offset:4096
	ds_read_b128 v[234:237], v184 offset:5120
	ds_read_b128 v[238:241], v184 offset:6144
	ds_read_b128 v[242:245], v184 offset:7168
	global_load_lds_dwordx4 v[168:169], off
	v_lshl_add_u64 v[168:169], v[164:165], 0, s[60:61]
	s_add_i32 m0, s69, 0xe000
	s_nop 0
	global_load_lds_dwordx4 v[168:169], off
	s_waitcnt vmcnt(8)
	s_waitcnt lgkmcnt(0)
	s_setprio 1
	s_barrier
; #define PG8_STAGE(bufoff, gbase, voff) do { _Pragma("unroll") for (int _i = 0; _i < 2; ++_i) \
;         __builtin_amdgcn_global_load_lds((const unsigned*)((const char*)(gbase) + (voff)[_i]), (PG8_LAS unsigned*)(lds + (bufoff) + ldsw + _i * 8192), 16, 0, 0); } while (0)
; #define PG8_LDA(dst, b, h) do { _Pragma("unroll") for (int m = 0; m < 4; ++m) _Pragma("unroll") for (int k = 0; k < 2; ++k) dst[m][k] = *(const PG8_LAS bf16x8*)(lds + PG8_SA(b, h) + aoff + m * 2048 + k * 1024); } while (0)
; #define PG8_MMA(ai, bj, At, Bt) do { __builtin_amdgcn_s_setprio(1); _Pragma("unroll") for (int m = 0; m < 4; ++m) _Pragma("unroll") for (int n = 0; n < 2; ++n) _Pragma("unroll") for (int k = 0; k < 2; ++k) \
;         acc[ai][bj][m][n] = __builtin_amdgcn_mfma_f32_16x16x32_bf16(Bt[n][k], At[m][k], acc[ai][bj][m][n], 0, 0, 0); __builtin_amdgcn_s_setprio(0); } while (0)
; #define PG8_WAIT_V(n) asm volatile("s_waitcnt vmcnt(" #n ")" ::: "memory")
; #define PG8_WAIT_L(n) asm volatile("s_waitcnt lgkmcnt(" #n ")" ::: "memory")
; #define PG8_BAR __builtin_amdgcn_s_barrier()
; #define PG8_SCHED __builtin_amdgcn_sched_barrier(0)
; template <class Epi, class Sched, bool ALIGN_EPI = false, bool SP2 = false>
; __device__ __forceinline__ void gemm_phase(PG8_LAS unsigned char* lds, const Gemm g, const Sched& S, const Epi& E) {
;     ...
;             PG8_WAIT_V(8); PG8_WAIT_L(0); PG8_BAR; PG8_MMA(0, 0, At, B0); PG8_MMA(0, 1, At, B1); PG8_BAR; PG8_SCHED;
;             PG8_LDA(At, 0, 1); PG8_STAGE(PG8_SB(0, 0), b2, voffB); PG8_STAGE(PG8_SB(0, 1), b2 + hstep, voffB); PG8_STAGE(PG8_SA(0, 0), a2, voffA);
;             PG8_WAIT_V(8); PG8_WAIT_L(0); PG8_BAR; PG8_MMA(1, 0, At, B0); PG8_MMA(1, 1, At, B1); PG8_BAR; PG8_SCHED;
	v_mfma_f32_16x16x32_bf16 v[126:129], v[130:133], v[214:217], v[126:129]
	v_mfma_f32_16x16x32_bf16 v[122:125], v[186:189], v[214:217], v[122:125]
	v_mfma_f32_16x16x32_bf16 v[110:113], v[130:133], v[222:225], v[110:113]
	v_mfma_f32_16x16x32_bf16 v[106:109], v[186:189], v[222:225], v[106:109]
	v_mfma_f32_16x16x32_bf16 v[94:97], v[130:133], v[230:233], v[94:97]
	v_mfma_f32_16x16x32_bf16 v[90:93], v[186:189], v[230:233], v[90:93]
	v_mfma_f32_16x16x32_bf16 v[78:81], v[130:133], v[238:241], v[78:81]
	v_mfma_f32_16x16x32_bf16 v[74:77], v[186:189], v[238:241], v[74:77]
	v_mfma_f32_16x16x32_bf16 v[126:129], v[134:137], v[218:221], v[126:129]
	v_mfma_f32_16x16x32_bf16 v[122:125], v[190:193], v[218:221], v[122:125]
	v_mfma_f32_16x16x32_bf16 v[110:113], v[134:137], v[226:229], v[110:113]
	v_mfma_f32_16x16x32_bf16 v[106:109], v[190:193], v[226:229], v[106:109]
	v_mfma_f32_16x16x32_bf16 v[94:97], v[134:137], v[234:237], v[94:97]
	v_mfma_f32_16x16x32_bf16 v[90:93], v[190:193], v[234:237], v[90:93]
	v_mfma_f32_16x16x32_bf16 v[78:81], v[134:137], v[242:245], v[78:81]
	v_mfma_f32_16x16x32_bf16 v[74:77], v[190:193], v[242:245], v[74:77]
	s_setprio 0
	s_setprio 1
	v_mfma_f32_16x16x32_bf16 v[118:121], v[194:197], v[214:217], v[118:121]
	v_mfma_f32_16x16x32_bf16 v[114:117], v[202:205], v[214:217], v[114:117]
	v_mfma_f32_16x16x32_bf16 v[102:105], v[194:197], v[222:225], v[102:105]
	v_mfma_f32_16x16x32_bf16 v[98:101], v[202:205], v[222:225], v[98:101]
	v_mfma_f32_16x16x32_bf16 v[86:89], v[194:197], v[230:233], v[86:89]
	v_mfma_f32_16x16x32_bf16 v[82:85], v[202:205], v[230:233], v[82:85]
	v_mfma_f32_16x16x32_bf16 v[70:73], v[194:197], v[238:241], v[70:73]
	v_mfma_f32_16x16x32_bf16 v[66:69], v[202:205], v[238:241], v[66:69]
	v_mfma_f32_16x16x32_bf16 v[118:121], v[198:201], v[218:221], v[118:121]
	v_mfma_f32_16x16x32_bf16 v[114:117], v[206:209], v[218:221], v[114:117]
	v_mfma_f32_16x16x32_bf16 v[102:105], v[198:201], v[226:229], v[102:105]
	v_mfma_f32_16x16x32_bf16 v[98:101], v[206:209], v[226:229], v[98:101]
	v_mfma_f32_16x16x32_bf16 v[86:89], v[198:201], v[234:237], v[86:89]
	v_mfma_f32_16x16x32_bf16 v[82:85], v[206:209], v[234:237], v[82:85]
	v_mfma_f32_16x16x32_bf16 v[70:73], v[198:201], v[242:245], v[70:73]
	v_mfma_f32_16x16x32_bf16 v[66:69], v[206:209], v[242:245], v[66:69]
	s_setprio 0
	s_barrier
	s_add_i32 s79, s79, s68
	v_lshl_add_u64 v[168:169], s[62:63], 0, v[0:1]
	s_mov_b32 m0, s79
	ds_read_b128 v[214:217], v184 offset:16384
	ds_read_b128 v[218:221], v184 offset:17408
	ds_read_b128 v[222:225], v184 offset:18432
	ds_read_b128 v[226:229], v184 offset:19456
	ds_read_b128 v[230:233], v184 offset:20480
	ds_read_b128 v[234:237], v184 offset:21504
	ds_read_b128 v[238:241], v184 offset:22528
	ds_read_b128 v[242:245], v184 offset:23552
	global_load_lds_dwordx4 v[168:169], off
	s_add_i32 m0, s79, 0x2000
	s_add_u32 s82, s62, 0x80000
	v_lshl_add_u64 v[246:247], s[62:63], 0, v[150:151]
	s_addc_u32 s83, s63, 0
	s_add_i32 s79, s86, s68
	global_load_lds_dwordx4 v[246:247], off
	v_lshl_add_u64 v[248:249], s[82:83], 0, v[0:1]
	s_mov_b32 m0, s79
	v_lshl_add_u64 v[142:143], s[64:65], 0, v[152:153]
	global_load_lds_dwordx4 v[248:249], off
	v_lshl_add_u64 v[248:249], s[82:83], 0, v[150:151]
	s_add_i32 m0, s79, 0x2000
	s_nop 0
	global_load_lds_dwordx4 v[248:249], off
	v_lshl_add_u64 v[248:249], s[64:65], 0, v[154:155]
	s_mov_b32 m0, s69
	s_nop 0
	global_load_lds_dwordx4 v[248:249], off
	s_mov_b32 m0, s70
	s_nop 0
	global_load_lds_dwordx4 v[142:143], off
	s_waitcnt vmcnt(8)
	s_waitcnt lgkmcnt(0)
	s_setprio 1
	s_barrier
	v_mfma_f32_16x16x32_bf16 v[62:65], v[130:133], v[214:217], v[62:65]
	v_mfma_f32_16x16x32_bf16 v[58:61], v[186:189], v[214:217], v[58:61]
	v_mfma_f32_16x16x32_bf16 v[46:49], v[130:133], v[222:225], v[46:49]
	v_mfma_f32_16x16x32_bf16 v[42:45], v[186:189], v[222:225], v[42:45]
	v_mfma_f32_16x16x32_bf16 v[30:33], v[130:133], v[230:233], v[30:33]
	v_mfma_f32_16x16x32_bf16 v[26:29], v[186:189], v[230:233], v[26:29]
	v_mfma_f32_16x16x32_bf16 v[14:17], v[130:133], v[238:241], v[14:17]
	v_mfma_f32_16x16x32_bf16 v[10:13], v[186:189], v[238:241], v[10:13]
	v_mfma_f32_16x16x32_bf16 v[62:65], v[134:137], v[218:221], v[62:65]
	v_mfma_f32_16x16x32_bf16 v[58:61], v[190:193], v[218:221], v[58:61]
	v_mfma_f32_16x16x32_bf16 v[46:49], v[134:137], v[226:229], v[46:49]
	v_mfma_f32_16x16x32_bf16 v[42:45], v[190:193], v[226:229], v[42:45]
	v_mfma_f32_16x16x32_bf16 v[30:33], v[134:137], v[234:237], v[30:33]
	v_mfma_f32_16x16x32_bf16 v[26:29], v[190:193], v[234:237], v[26:29]
	v_mfma_f32_16x16x32_bf16 v[14:17], v[134:137], v[242:245], v[14:17]
	v_mfma_f32_16x16x32_bf16 v[10:13], v[190:193], v[242:245], v[10:13]
	s_setprio 0
	s_setprio 1
	v_mfma_f32_16x16x32_bf16 v[54:57], v[194:197], v[214:217], v[54:57]
	v_mfma_f32_16x16x32_bf16 v[50:53], v[202:205], v[214:217], v[50:53]
	v_mfma_f32_16x16x32_bf16 v[38:41], v[194:197], v[222:225], v[38:41]
	v_mfma_f32_16x16x32_bf16 v[34:37], v[202:205], v[222:225], v[34:37]
	v_mfma_f32_16x16x32_bf16 v[22:25], v[194:197], v[230:233], v[22:25]
	v_mfma_f32_16x16x32_bf16 v[18:21], v[202:205], v[230:233], v[18:21]
	v_mfma_f32_16x16x32_bf16 v[6:9], v[194:197], v[238:241], v[6:9]
	v_mfma_f32_16x16x32_bf16 v[2:5], v[202:205], v[238:241], v[2:5]
	v_mfma_f32_16x16x32_bf16 v[54:57], v[198:201], v[218:221], v[54:57]
	v_mfma_f32_16x16x32_bf16 v[50:53], v[206:209], v[218:221], v[50:53]
	v_mfma_f32_16x16x32_bf16 v[38:41], v[198:201], v[226:229], v[38:41]
	v_mfma_f32_16x16x32_bf16 v[34:37], v[206:209], v[226:229], v[34:37]
	v_mfma_f32_16x16x32_bf16 v[22:25], v[198:201], v[234:237], v[22:25]
	v_mfma_f32_16x16x32_bf16 v[18:21], v[206:209], v[234:237], v[18:21]
	v_mfma_f32_16x16x32_bf16 v[6:9], v[198:201], v[242:245], v[6:9]
	v_mfma_f32_16x16x32_bf16 v[2:5], v[206:209], v[242:245], v[2:5]
	s_setprio 0
	s_barrier
; #define PG8_STAGE(bufoff, gbase, voff) do { _Pragma("unroll") for (int _i = 0; _i < 2; ++_i) \
;         __builtin_amdgcn_global_load_lds((const unsigned*)((const char*)(gbase) + (voff)[_i]), (PG8_LAS unsigned*)(lds + (bufoff) + ldsw + _i * 8192), 16, 0, 0); } while (0)
; #define PG8_LDA(dst, b, h) do { _Pragma("unroll") for (int m = 0; m < 4; ++m) _Pragma("unroll") for (int k = 0; k < 2; ++k) dst[m][k] = *(const PG8_LAS bf16x8*)(lds + PG8_SA(b, h) + aoff + m * 2048 + k * 1024); } while (0)
; #define PG8_LDB(dst, b, h) do { _Pragma("unroll") for (int n = 0; n < 2; ++n) _Pragma("unroll") for (int k = 0; k < 2; ++k) dst[n][k] = *(const PG8_LAS bf16x8*)(lds + PG8_SB(b, h) + boff + n * 2048 + k * 1024); } while (0)
; #define PG8_MMA(ai, bj, At, Bt) do { __builtin_amdgcn_s_setprio(1); _Pragma("unroll") for (int m = 0; m < 4; ++m) _Pragma("unroll") for (int n = 0; n < 2; ++n) _Pragma("unroll") for (int k = 0; k < 2; ++k) \
;         acc[ai][bj][m][n] = __builtin_amdgcn_mfma_f32_16x16x32_bf16(Bt[n][k], At[m][k], acc[ai][bj][m][n], 0, 0, 0); __builtin_amdgcn_s_setprio(0); } while (0)
; #define PG8_WAIT_V(n) asm volatile("s_waitcnt vmcnt(" #n ")" ::: "memory")
; #define PG8_WAIT_L(n) asm volatile("s_waitcnt lgkmcnt(" #n ")" ::: "memory")
; #define PG8_BAR __builtin_amdgcn_s_barrier()
; #define PG8_SCHED __builtin_amdgcn_sched_barrier(0)
; template <class Epi, class Sched, bool ALIGN_EPI = false, bool SP2 = false>
; __device__ __forceinline__ void gemm_phase(PG8_LAS unsigned char* lds, const Gemm g, const Sched& S, const Epi& E) {
;     ...
;             PG8_LDB(B0, 1, 0); PG8_LDB(B1, 1, 1); PG8_SCHED; PG8_LDA(At, 1, 0); PG8_STAGE(PG8_SA(0, 1), a2 + hstep, voffA);
;             PG8_WAIT_V(8); PG8_WAIT_L(0); PG8_BAR; PG8_MMA(0, 0, At, B0); PG8_MMA(0, 1, At, B1); PG8_BAR; PG8_SCHED;
	s_add_i32 s79, 0, 0x18000
	v_add_u32_e32 v144, s79, v182
	s_add_i32 s82, 0, 0x1c000
	ds_read_b128 v[130:133], v144
	ds_read_b128 v[134:137], v144 offset:1024
	ds_read_b128 v[186:189], v144 offset:2048
	ds_read_b128 v[190:193], v144 offset:3072
	v_add_u32_e32 v144, s82, v182
	ds_read_b128 v[194:197], v144
	ds_read_b128 v[198:201], v144 offset:1024
	ds_read_b128 v[202:205], v144 offset:2048
	ds_read_b128 v[206:209], v144 offset:3072
	s_add_u32 s64, s64, 0x80000
	s_addc_u32 s65, s65, 0
	s_mov_b32 m0, s71
	v_lshl_add_u64 v[144:145], s[64:65], 0, v[154:155]
	ds_read_b128 v[214:217], v184 offset:32768
	ds_read_b128 v[218:221], v184 offset:33792
	ds_read_b128 v[222:225], v184 offset:34816
	ds_read_b128 v[226:229], v184 offset:35840
	ds_read_b128 v[230:233], v184 offset:36864
	ds_read_b128 v[234:237], v184 offset:37888
	ds_read_b128 v[238:241], v184 offset:38912
	ds_read_b128 v[242:245], v184 offset:39936
	global_load_lds_dwordx4 v[144:145], off
	v_lshl_add_u64 v[144:145], s[64:65], 0, v[152:153]
	s_mov_b32 m0, s72
	s_nop 0
	global_load_lds_dwordx4 v[144:145], off
	s_waitcnt vmcnt(8)
	s_waitcnt lgkmcnt(0)
	s_setprio 1
	s_barrier
	v_mfma_f32_16x16x32_bf16 v[126:129], v[130:133], v[214:217], v[126:129]
	v_mfma_f32_16x16x32_bf16 v[122:125], v[186:189], v[214:217], v[122:125]
	v_mfma_f32_16x16x32_bf16 v[110:113], v[130:133], v[222:225], v[110:113]
	v_mfma_f32_16x16x32_bf16 v[106:109], v[186:189], v[222:225], v[106:109]
	v_mfma_f32_16x16x32_bf16 v[94:97], v[130:133], v[230:233], v[94:97]
	v_mfma_f32_16x16x32_bf16 v[90:93], v[186:189], v[230:233], v[90:93]
	v_mfma_f32_16x16x32_bf16 v[78:81], v[130:133], v[238:241], v[78:81]
	v_mfma_f32_16x16x32_bf16 v[74:77], v[186:189], v[238:241], v[74:77]
	v_mfma_f32_16x16x32_bf16 v[126:129], v[134:137], v[218:221], v[126:129]
	v_mfma_f32_16x16x32_bf16 v[122:125], v[190:193], v[218:221], v[122:125]
	v_mfma_f32_16x16x32_bf16 v[110:113], v[134:137], v[226:229], v[110:113]
	v_mfma_f32_16x16x32_bf16 v[106:109], v[190:193], v[226:229], v[106:109]
	v_mfma_f32_16x16x32_bf16 v[94:97], v[134:137], v[234:237], v[94:97]
	v_mfma_f32_16x16x32_bf16 v[90:93], v[190:193], v[234:237], v[90:93]
	v_mfma_f32_16x16x32_bf16 v[78:81], v[134:137], v[242:245], v[78:81]
	v_mfma_f32_16x16x32_bf16 v[74:77], v[190:193], v[242:245], v[74:77]
	s_setprio 0
	s_setprio 1
	v_mfma_f32_16x16x32_bf16 v[118:121], v[194:197], v[214:217], v[118:121]
	v_mfma_f32_16x16x32_bf16 v[114:117], v[202:205], v[214:217], v[114:117]
	v_mfma_f32_16x16x32_bf16 v[102:105], v[194:197], v[222:225], v[102:105]
	v_mfma_f32_16x16x32_bf16 v[98:101], v[202:205], v[222:225], v[98:101]
	v_mfma_f32_16x16x32_bf16 v[86:89], v[194:197], v[230:233], v[86:89]
	v_mfma_f32_16x16x32_bf16 v[82:85], v[202:205], v[230:233], v[82:85]
	v_mfma_f32_16x16x32_bf16 v[70:73], v[194:197], v[238:241], v[70:73]
	v_mfma_f32_16x16x32_bf16 v[66:69], v[202:205], v[238:241], v[66:69]
	v_mfma_f32_16x16x32_bf16 v[118:121], v[198:201], v[218:221], v[118:121]
	v_mfma_f32_16x16x32_bf16 v[114:117], v[206:209], v[218:221], v[114:117]
	v_mfma_f32_16x16x32_bf16 v[102:105], v[198:201], v[226:229], v[102:105]
	v_mfma_f32_16x16x32_bf16 v[98:101], v[206:209], v[226:229], v[98:101]
	v_mfma_f32_16x16x32_bf16 v[86:89], v[198:201], v[234:237], v[86:89]
	v_mfma_f32_16x16x32_bf16 v[82:85], v[206:209], v[234:237], v[82:85]
	v_mfma_f32_16x16x32_bf16 v[70:73], v[198:201], v[242:245], v[70:73]
	v_mfma_f32_16x16x32_bf16 v[66:69], v[206:209], v[242:245], v[66:69]
	s_setprio 0
	s_barrier
; #define PG8_STAGE(bufoff, gbase, voff) do { _Pragma("unroll") for (int _i = 0; _i < 2; ++_i) \
;         __builtin_amdgcn_global_load_lds((const unsigned*)((const char*)(gbase) + (voff)[_i]), (PG8_LAS unsigned*)(lds + (bufoff) + ldsw + _i * 8192), 16, 0, 0); } while (0)
; #define PG8_LDA(dst, b, h) do { _Pragma("unroll") for (int m = 0; m < 4; ++m) _Pragma("unroll") for (int k = 0; k < 2; ++k) dst[m][k] = *(const PG8_LAS bf16x8*)(lds + PG8_SA(b, h) + aoff + m * 2048 + k * 1024); } while (0)
; #define PG8_MMA(ai, bj, At, Bt) do { __builtin_amdgcn_s_setprio(1); _Pragma("unroll") for (int m = 0; m < 4; ++m) _Pragma("unroll") for (int n = 0; n < 2; ++n) _Pragma("unroll") for (int k = 0; k < 2; ++k) \
;         acc[ai][bj][m][n] = __builtin_amdgcn_mfma_f32_16x16x32_bf16(Bt[n][k], At[m][k], acc[ai][bj][m][n], 0, 0, 0); __builtin_amdgcn_s_setprio(0); } while (0)
; #define PG8_WAIT_V(n) asm volatile("s_waitcnt vmcnt(" #n ")" ::: "memory")
; #define PG8_WAIT_L(n) asm volatile("s_waitcnt lgkmcnt(" #n ")" ::: "memory")
; #define PG8_BAR __builtin_amdgcn_s_barrier()
; #define PG8_SCHED __builtin_amdgcn_sched_barrier(0)
; template <class Epi, class Sched, bool ALIGN_EPI = false, bool SP2 = false>
; __device__ __forceinline__ void gemm_phase(PG8_LAS unsigned char* lds, const Gemm g, const Sched& S, const Epi& E) {
;     ...
;         for (int t = 0; t < nt; t += 2) {
;             const bool last = (t == nt - 2);
;             const char* a1 = cA + (size_t)(t + 1) * kstep;
;             const char* a2 = last ? nA : cA + (size_t)(t + 2) * kstep; const char* b2 = last ? nB : cB + (size_t)(t + 2) * kstep;
;             const char* a3 = a2 + kstep; const char* b3 = b2 + kstep;
;             if (last && has_next) S.a_ready(nxt);
;             if constexpr (Epi::MID) { if (t == nt / 2) E.mid(acc, cur, wr, wc, fr, fq); }
;     ...
;             PG8_LDA(At, 1, 1); PG8_STAGE(PG8_SB(1, 0), b3, voffB); PG8_STAGE(PG8_SB(1, 1), b3 + hstep, voffB); PG8_STAGE(PG8_SA(1, 0), a3, voffA);
;             PG8_WAIT_V(8); PG8_WAIT_L(0); PG8_BAR; PG8_MMA(1, 0, At, B0); PG8_MMA(1, 1, At, B1); PG8_BAR; PG8_SCHED;
	s_add_i32 s64, s79, s68
	v_lshl_add_u64 v[144:145], v[168:169], 0, s[34:35]
	s_mov_b32 m0, s64
	ds_read_b128 v[214:217], v184 offset:49152
	ds_read_b128 v[218:221], v184 offset:50176
	ds_read_b128 v[222:225], v184 offset:51200
	ds_read_b128 v[226:229], v184 offset:52224
	ds_read_b128 v[230:233], v184 offset:53248
	ds_read_b128 v[234:237], v184 offset:54272
	ds_read_b128 v[238:241], v184 offset:55296
	ds_read_b128 v[242:245], v184 offset:56320
	global_load_lds_dwordx4 v[144:145], off
	s_add_i32 m0, s64, 0x2000
	s_add_u32 s62, s62, 0x80080
	v_lshl_add_u64 v[144:145], v[246:247], 0, s[34:35]
	s_addc_u32 s63, s63, 0
	s_add_i32 s64, s82, s68
	global_load_lds_dwordx4 v[144:145], off
	v_lshl_add_u64 v[144:145], s[62:63], 0, v[0:1]
	s_mov_b32 m0, s64
	v_lshl_add_u64 v[142:143], v[142:143], 0, s[34:35]
	global_load_lds_dwordx4 v[144:145], off
	v_lshl_add_u64 v[144:145], s[62:63], 0, v[150:151]
	s_add_i32 m0, s64, 0x2000
	s_nop 0
	global_load_lds_dwordx4 v[144:145], off
	v_lshl_add_u64 v[144:145], v[248:249], 0, s[34:35]
	s_mov_b32 m0, s73
	s_nop 0
	global_load_lds_dwordx4 v[144:145], off
	s_mov_b32 m0, s74
	s_nop 0
	global_load_lds_dwordx4 v[142:143], off
	s_waitcnt vmcnt(8)
	s_waitcnt lgkmcnt(0)
	s_setprio 1
	s_barrier
	v_mfma_f32_16x16x32_bf16 v[62:65], v[130:133], v[214:217], v[62:65]
	v_mfma_f32_16x16x32_bf16 v[58:61], v[186:189], v[214:217], v[58:61]
	v_mfma_f32_16x16x32_bf16 v[46:49], v[130:133], v[222:225], v[46:49]
	v_mfma_f32_16x16x32_bf16 v[42:45], v[186:189], v[222:225], v[42:45]
	v_mfma_f32_16x16x32_bf16 v[30:33], v[130:133], v[230:233], v[30:33]
	v_mfma_f32_16x16x32_bf16 v[26:29], v[186:189], v[230:233], v[26:29]
	v_mfma_f32_16x16x32_bf16 v[14:17], v[130:133], v[238:241], v[14:17]
	v_mfma_f32_16x16x32_bf16 v[10:13], v[186:189], v[238:241], v[10:13]
	v_mfma_f32_16x16x32_bf16 v[62:65], v[134:137], v[218:221], v[62:65]
	v_mfma_f32_16x16x32_bf16 v[58:61], v[190:193], v[218:221], v[58:61]
	v_mfma_f32_16x16x32_bf16 v[46:49], v[134:137], v[226:229], v[46:49]
	v_mfma_f32_16x16x32_bf16 v[42:45], v[190:193], v[226:229], v[42:45]
	v_mfma_f32_16x16x32_bf16 v[30:33], v[134:137], v[234:237], v[30:33]
	v_mfma_f32_16x16x32_bf16 v[26:29], v[190:193], v[234:237], v[26:29]
	v_mfma_f32_16x16x32_bf16 v[14:17], v[134:137], v[242:245], v[14:17]
	v_mfma_f32_16x16x32_bf16 v[10:13], v[190:193], v[242:245], v[10:13]
	s_setprio 0
	s_setprio 1
	v_mfma_f32_16x16x32_bf16 v[54:57], v[194:197], v[214:217], v[54:57]
	v_mfma_f32_16x16x32_bf16 v[50:53], v[202:205], v[214:217], v[50:53]
	v_mfma_f32_16x16x32_bf16 v[38:41], v[194:197], v[222:225], v[38:41]
	v_mfma_f32_16x16x32_bf16 v[34:37], v[202:205], v[222:225], v[34:37]
	v_mfma_f32_16x16x32_bf16 v[22:25], v[194:197], v[230:233], v[22:25]
	v_mfma_f32_16x16x32_bf16 v[18:21], v[202:205], v[230:233], v[18:21]
	v_mfma_f32_16x16x32_bf16 v[6:9], v[194:197], v[238:241], v[6:9]
	v_mfma_f32_16x16x32_bf16 v[2:5], v[202:205], v[238:241], v[2:5]
	v_mfma_f32_16x16x32_bf16 v[54:57], v[198:201], v[218:221], v[54:57]
	v_mfma_f32_16x16x32_bf16 v[50:53], v[206:209], v[218:221], v[50:53]
	v_mfma_f32_16x16x32_bf16 v[38:41], v[198:201], v[226:229], v[38:41]
	v_mfma_f32_16x16x32_bf16 v[34:37], v[206:209], v[226:229], v[34:37]
	v_mfma_f32_16x16x32_bf16 v[22:25], v[198:201], v[234:237], v[22:25]
	v_mfma_f32_16x16x32_bf16 v[18:21], v[206:209], v[234:237], v[18:21]
	v_mfma_f32_16x16x32_bf16 v[6:9], v[198:201], v[242:245], v[6:9]
	v_mfma_f32_16x16x32_bf16 v[2:5], v[206:209], v[242:245], v[2:5]
	s_setprio 0
	s_add_i32 s78, s78, 2
	s_add_u32 s60, s60, 0x100
	s_addc_u32 s61, s61, 0
	s_cmp_gt_u32 s78, 29
	s_cbranch_scc1 .Lg2_exit_bar
	s_cmpk_lg_i32 s60, 0x800
	s_cbranch_scc1 .Lg2_head_bar
	s_barrier
	s_branch .Lg2_mid
.Lg2_exit_bar:
	s_barrier
	s_branch .LBB0_80

; __device__ __forceinline__ float bflo(unsigned w) { return __uint_as_float(w << 16); }
; __device__ __forceinline__ float bfhi(unsigned w) { return __uint_as_float(w & 0xffff0000u); }
;     __device__ __forceinline__ void mid(f32x4 (&acc)[2][2][4][2], const Unit& u, int wr, int wc, int fr, int fq) const {
;         int row0 = u.pm * BM + wr * 64 + fr, col0 = u.pn * BM + wc * 32 + 8 * fq;
;         asm volatile("" : "+v"(row0), "+v"(col0));
; #pragma unroll
;         for (int ai = 0; ai < 2; ++ai)
; #pragma unroll
;             for (int m = 0; m < 4; ++m) { const size_t row = (size_t)(row0 + ai * HALF + m * 16);
; #pragma unroll
;                 for (int bj = 0; bj < 2; ++bj) { const int col = col0 + bj * HALF;
;                     const u32x4 ga = *(const u32x4*)(P + row * LDP + PC_GA + col), gb = *(const u32x4*)(P + row * LDP + PC_GB + col);
; #pragma unroll
;                     for (int j = 0; j < 2; ++j) {
;                         acc[ai][bj][m][0][2 * j] *= bflo(ga[j]) * __builtin_amdgcn_rcpf(bflo(gb[j])); acc[ai][bj][m][0][2 * j + 1] *= bfhi(ga[j]) * __builtin_amdgcn_rcpf(bfhi(gb[j]));
;                         acc[ai][bj][m][1][2 * j] *= bflo(ga[2 + j]) * __builtin_amdgcn_rcpf(bflo(gb[2 + j])); acc[ai][bj][m][1][2 * j + 1] *= bfhi(ga[2 + j]) * __builtin_amdgcn_rcpf(bfhi(gb[2 + j])); } }
;                 asm volatile("" ::: "memory"); }
.Lg2_mid:
	v_mul_u32_u24_e32 v161, 0x6200, v160
	v_lshl_add_u32 v161, v162, 1, v161
	s_add_u32 s62, s40, 0x4a00
	s_addc_u32 s63, s41, 0
	global_load_dwordx4 v[130:133], v161, s[62:63] offset:-2048
	global_load_dwordx4 v[134:137], v161, s[62:63] offset:2048
	s_add_u32 s62, s40, 0x4b00
	s_addc_u32 s63, s41, 0
	global_load_dwordx4 v[186:189], v161, s[62:63] offset:-2048
	global_load_dwordx4 v[190:193], v161, s[62:63] offset:2048
	s_add_u32 s62, s40, 0x66a00
	s_addc_u32 s63, s41, 0
	global_load_dwordx4 v[194:197], v161, s[62:63] offset:-2048
	global_load_dwordx4 v[198:201], v161, s[62:63] offset:2048
	s_add_u32 s62, s40, 0x66b00
	s_addc_u32 s63, s41, 0
	global_load_dwordx4 v[202:205], v161, s[62:63] offset:-2048
	global_load_dwordx4 v[206:209], v161, s[62:63] offset:2048
	s_add_u32 s62, s40, 0xc8a00
	s_addc_u32 s63, s41, 0
	global_load_dwordx4 v[214:217], v161, s[62:63] offset:-2048
	global_load_dwordx4 v[218:221], v161, s[62:63] offset:2048
	s_add_u32 s62, s40, 0xc8b00
	s_addc_u32 s63, s41, 0
	global_load_dwordx4 v[222:225], v161, s[62:63] offset:-2048
	global_load_dwordx4 v[226:229], v161, s[62:63] offset:2048
	s_add_u32 s62, s40, 0x12aa00
	s_addc_u32 s63, s41, 0
	global_load_dwordx4 v[230:233], v161, s[62:63] offset:-2048
	global_load_dwordx4 v[234:237], v161, s[62:63] offset:2048
	s_add_u32 s62, s40, 0x12ab00
	s_addc_u32 s63, s41, 0
	global_load_dwordx4 v[238:241], v161, s[62:63] offset:-2048
	global_load_dwordx4 v[242:245], v161, s[62:63] offset:2048
	s_waitcnt vmcnt(14)
	v_lshlrev_b32_e32 v144, 16, v134
	v_and_b32_e32 v145, 0xffff0000, v134
	v_lshlrev_b32_e32 v168, 16, v135
	v_and_b32_e32 v169, 0xffff0000, v135
	v_rcp_f32_e32 v144, v144
	v_rcp_f32_e32 v145, v145
	v_rcp_f32_e32 v168, v168
	v_rcp_f32_e32 v169, v169
	v_lshlrev_b32_e32 v142, 16, v130
	v_and_b32_e32 v143, 0xffff0000, v130
	v_pk_mul_f32 v[144:145], v[144:145], v[142:143]
	v_lshlrev_b32_e32 v142, 16, v131
	v_and_b32_e32 v143, 0xffff0000, v131
	v_pk_mul_f32 v[168:169], v[168:169], v[142:143]
	v_pk_mul_f32 v[126:127], v[126:127], v[144:145]
	v_pk_mul_f32 v[128:129], v[128:129], v[168:169]
	v_lshlrev_b32_e32 v144, 16, v136
	v_and_b32_e32 v145, 0xffff0000, v136
	v_lshlrev_b32_e32 v168, 16, v137
	v_and_b32_e32 v169, 0xffff0000, v137
	v_rcp_f32_e32 v144, v144
	v_rcp_f32_e32 v145, v145
	v_rcp_f32_e32 v168, v168
	v_rcp_f32_e32 v169, v169
	v_lshlrev_b32_e32 v142, 16, v132
	v_and_b32_e32 v143, 0xffff0000, v132
	v_pk_mul_f32 v[144:145], v[144:145], v[142:143]
	v_lshlrev_b32_e32 v142, 16, v133
	v_and_b32_e32 v143, 0xffff0000, v133
	v_pk_mul_f32 v[168:169], v[168:169], v[142:143]
	v_pk_mul_f32 v[122:123], v[122:123], v[144:145]
	v_pk_mul_f32 v[124:125], v[124:125], v[168:169]
	s_add_u32 s62, s40, 0x314a00
	s_addc_u32 s63, s41, 0
	global_load_dwordx4 v[130:133], v161, s[62:63] offset:-2048
	global_load_dwordx4 v[134:137], v161, s[62:63] offset:2048
	s_waitcnt vmcnt(14)
	v_lshlrev_b32_e32 v144, 16, v190
	v_and_b32_e32 v145, 0xffff0000, v190
	v_lshlrev_b32_e32 v168, 16, v191
	v_and_b32_e32 v169, 0xffff0000, v191
	v_rcp_f32_e32 v144, v144
	v_rcp_f32_e32 v145, v145
	v_rcp_f32_e32 v168, v168
	v_rcp_f32_e32 v169, v169
	v_lshlrev_b32_e32 v142, 16, v186
	v_and_b32_e32 v143, 0xffff0000, v186
	v_pk_mul_f32 v[144:145], v[144:145], v[142:143]
	v_lshlrev_b32_e32 v142, 16, v187
	v_and_b32_e32 v143, 0xffff0000, v187
	v_pk_mul_f32 v[168:169], v[168:169], v[142:143]
	v_pk_mul_f32 v[118:119], v[118:119], v[144:145]
	v_pk_mul_f32 v[120:121], v[120:121], v[168:169]
	v_lshlrev_b32_e32 v144, 16, v192
	v_and_b32_e32 v145, 0xffff0000, v192
	v_lshlrev_b32_e32 v168, 16, v193
	v_and_b32_e32 v169, 0xffff0000, v193
	v_rcp_f32_e32 v144, v144
	v_rcp_f32_e32 v145, v145
	v_rcp_f32_e32 v168, v168
	v_rcp_f32_e32 v169, v169
	v_lshlrev_b32_e32 v142, 16, v188
	v_and_b32_e32 v143, 0xffff0000, v188
	v_pk_mul_f32 v[144:145], v[144:145], v[142:143]
	v_lshlrev_b32_e32 v142, 16, v189
	v_and_b32_e32 v143, 0xffff0000, v189
	v_pk_mul_f32 v[168:169], v[168:169], v[142:143]
	v_pk_mul_f32 v[114:115], v[114:115], v[144:145]
	v_pk_mul_f32 v[116:117], v[116:117], v[168:169]
	s_add_u32 s62, s40, 0x314b00
	s_addc_u32 s63, s41, 0
	global_load_dwordx4 v[186:189], v161, s[62:63] offset:-2048
	global_load_dwordx4 v[190:193], v161, s[62:63] offset:2048
	s_waitcnt vmcnt(14)
	v_lshlrev_b32_e32 v144, 16, v198
	v_and_b32_e32 v145, 0xffff0000, v198
	v_lshlrev_b32_e32 v168, 16, v199
	v_and_b32_e32 v169, 0xffff0000, v199
	v_rcp_f32_e32 v144, v144
	v_rcp_f32_e32 v145, v145
	v_rcp_f32_e32 v168, v168
	v_rcp_f32_e32 v169, v169
	v_lshlrev_b32_e32 v142, 16, v194
	v_and_b32_e32 v143, 0xffff0000, v194
	v_pk_mul_f32 v[144:145], v[144:145], v[142:143]
	v_lshlrev_b32_e32 v142, 16, v195
	v_and_b32_e32 v143, 0xffff0000, v195
	v_pk_mul_f32 v[168:169], v[168:169], v[142:143]
	v_pk_mul_f32 v[110:111], v[110:111], v[144:145]
	v_pk_mul_f32 v[112:113], v[112:113], v[168:169]
	v_lshlrev_b32_e32 v144, 16, v200
	v_and_b32_e32 v145, 0xffff0000, v200
	v_lshlrev_b32_e32 v168, 16, v201
	v_and_b32_e32 v169, 0xffff0000, v201
	v_rcp_f32_e32 v144, v144
	v_rcp_f32_e32 v145, v145
	v_rcp_f32_e32 v168, v168
	v_rcp_f32_e32 v169, v169
	v_lshlrev_b32_e32 v142, 16, v196
	v_and_b32_e32 v143, 0xffff0000, v196
	v_pk_mul_f32 v[144:145], v[144:145], v[142:143]
	v_lshlrev_b32_e32 v142, 16, v197
	v_and_b32_e32 v143, 0xffff0000, v197
	v_pk_mul_f32 v[168:169], v[168:169], v[142:143]
	v_pk_mul_f32 v[106:107], v[106:107], v[144:145]
	v_pk_mul_f32 v[108:109], v[108:109], v[168:169]
	s_add_u32 s62, s40, 0x376a00
	s_addc_u32 s63, s41, 0
	global_load_dwordx4 v[194:197], v161, s[62:63] offset:-2048
	global_load_dwordx4 v[198:201], v161, s[62:63] offset:2048
	s_waitcnt vmcnt(14)
; __device__ __forceinline__ float bflo(unsigned w) { return __uint_as_float(w << 16); }
; __device__ __forceinline__ float bfhi(unsigned w) { return __uint_as_float(w & 0xffff0000u); }
;     __device__ __forceinline__ void mid(f32x4 (&acc)[2][2][4][2], const Unit& u, int wr, int wc, int fr, int fq) const {
;         int row0 = u.pm * BM + wr * 64 + fr, col0 = u.pn * BM + wc * 32 + 8 * fq;
;         asm volatile("" : "+v"(row0), "+v"(col0));
; #pragma unroll
;         for (int ai = 0; ai < 2; ++ai)
; #pragma unroll
;             for (int m = 0; m < 4; ++m) { const size_t row = (size_t)(row0 + ai * HALF + m * 16);
; #pragma unroll
;                 for (int bj = 0; bj < 2; ++bj) { const int col = col0 + bj * HALF;
;                     const u32x4 ga = *(const u32x4*)(P + row * LDP + PC_GA + col), gb = *(const u32x4*)(P + row * LDP + PC_GB + col);
; #pragma unroll
;                     for (int j = 0; j < 2; ++j) {
;                         acc[ai][bj][m][0][2 * j] *= bflo(ga[j]) * __builtin_amdgcn_rcpf(bflo(gb[j])); acc[ai][bj][m][0][2 * j + 1] *= bfhi(ga[j]) * __builtin_amdgcn_rcpf(bfhi(gb[j]));
;                         acc[ai][bj][m][1][2 * j] *= bflo(ga[2 + j]) * __builtin_amdgcn_rcpf(bflo(gb[2 + j])); acc[ai][bj][m][1][2 * j + 1] *= bfhi(ga[2 + j]) * __builtin_amdgcn_rcpf(bfhi(gb[2 + j])); } }
;                 asm volatile("" ::: "memory"); }
	v_lshlrev_b32_e32 v144, 16, v206
	v_and_b32_e32 v145, 0xffff0000, v206
	v_lshlrev_b32_e32 v168, 16, v207
	v_and_b32_e32 v169, 0xffff0000, v207
	v_rcp_f32_e32 v144, v144
	v_rcp_f32_e32 v145, v145
	v_rcp_f32_e32 v168, v168
	v_rcp_f32_e32 v169, v169
	v_lshlrev_b32_e32 v142, 16, v202
	v_and_b32_e32 v143, 0xffff0000, v202
	v_pk_mul_f32 v[144:145], v[144:145], v[142:143]
	v_lshlrev_b32_e32 v142, 16, v203
	v_and_b32_e32 v143, 0xffff0000, v203
	v_pk_mul_f32 v[168:169], v[168:169], v[142:143]
	v_pk_mul_f32 v[102:103], v[102:103], v[144:145]
	v_pk_mul_f32 v[104:105], v[104:105], v[168:169]
	v_lshlrev_b32_e32 v144, 16, v208
	v_and_b32_e32 v145, 0xffff0000, v208
	v_lshlrev_b32_e32 v168, 16, v209
	v_and_b32_e32 v169, 0xffff0000, v209
	v_rcp_f32_e32 v144, v144
	v_rcp_f32_e32 v145, v145
	v_rcp_f32_e32 v168, v168
	v_rcp_f32_e32 v169, v169
	v_lshlrev_b32_e32 v142, 16, v204
	v_and_b32_e32 v143, 0xffff0000, v204
	v_pk_mul_f32 v[144:145], v[144:145], v[142:143]
	v_lshlrev_b32_e32 v142, 16, v205
	v_and_b32_e32 v143, 0xffff0000, v205
	v_pk_mul_f32 v[168:169], v[168:169], v[142:143]
	v_pk_mul_f32 v[98:99], v[98:99], v[144:145]
	v_pk_mul_f32 v[100:101], v[100:101], v[168:169]
	s_add_u32 s62, s40, 0x376b00
	s_addc_u32 s63, s41, 0
	global_load_dwordx4 v[202:205], v161, s[62:63] offset:-2048
	global_load_dwordx4 v[206:209], v161, s[62:63] offset:2048
	s_waitcnt vmcnt(14)
	v_lshlrev_b32_e32 v144, 16, v218
	v_and_b32_e32 v145, 0xffff0000, v218
	v_lshlrev_b32_e32 v168, 16, v219
	v_and_b32_e32 v169, 0xffff0000, v219
	v_rcp_f32_e32 v144, v144
	v_rcp_f32_e32 v145, v145
	v_rcp_f32_e32 v168, v168
	v_rcp_f32_e32 v169, v169
	v_lshlrev_b32_e32 v142, 16, v214
	v_and_b32_e32 v143, 0xffff0000, v214
	v_pk_mul_f32 v[144:145], v[144:145], v[142:143]
	v_lshlrev_b32_e32 v142, 16, v215
	v_and_b32_e32 v143, 0xffff0000, v215
	v_pk_mul_f32 v[168:169], v[168:169], v[142:143]
	v_pk_mul_f32 v[94:95], v[94:95], v[144:145]
	v_pk_mul_f32 v[96:97], v[96:97], v[168:169]
	v_lshlrev_b32_e32 v144, 16, v220
	v_and_b32_e32 v145, 0xffff0000, v220
	v_lshlrev_b32_e32 v168, 16, v221
	v_and_b32_e32 v169, 0xffff0000, v221
	v_rcp_f32_e32 v144, v144
	v_rcp_f32_e32 v145, v145
	v_rcp_f32_e32 v168, v168
	v_rcp_f32_e32 v169, v169
	v_lshlrev_b32_e32 v142, 16, v216
	v_and_b32_e32 v143, 0xffff0000, v216
	v_pk_mul_f32 v[144:145], v[144:145], v[142:143]
	v_lshlrev_b32_e32 v142, 16, v217
	v_and_b32_e32 v143, 0xffff0000, v217
	v_pk_mul_f32 v[168:169], v[168:169], v[142:143]
	v_pk_mul_f32 v[90:91], v[90:91], v[144:145]
	v_pk_mul_f32 v[92:93], v[92:93], v[168:169]
	s_add_u32 s62, s40, 0x3d8a00
	s_addc_u32 s63, s41, 0
	global_load_dwordx4 v[214:217], v161, s[62:63] offset:-2048
	global_load_dwordx4 v[218:221], v161, s[62:63] offset:2048
	s_waitcnt vmcnt(14)
	v_lshlrev_b32_e32 v144, 16, v226
	v_and_b32_e32 v145, 0xffff0000, v226
	v_lshlrev_b32_e32 v168, 16, v227
	v_and_b32_e32 v169, 0xffff0000, v227
	v_rcp_f32_e32 v144, v144
	v_rcp_f32_e32 v145, v145
	v_rcp_f32_e32 v168, v168
	v_rcp_f32_e32 v169, v169
	v_lshlrev_b32_e32 v142, 16, v222
	v_and_b32_e32 v143, 0xffff0000, v222
	v_pk_mul_f32 v[144:145], v[144:145], v[142:143]
	v_lshlrev_b32_e32 v142, 16, v223
	v_and_b32_e32 v143, 0xffff0000, v223
	v_pk_mul_f32 v[168:169], v[168:169], v[142:143]
	v_pk_mul_f32 v[86:87], v[86:87], v[144:145]
	v_pk_mul_f32 v[88:89], v[88:89], v[168:169]
	v_lshlrev_b32_e32 v144, 16, v228
	v_and_b32_e32 v145, 0xffff0000, v228
	v_lshlrev_b32_e32 v168, 16, v229
	v_and_b32_e32 v169, 0xffff0000, v229
	v_rcp_f32_e32 v144, v144
	v_rcp_f32_e32 v145, v145
	v_rcp_f32_e32 v168, v168
	v_rcp_f32_e32 v169, v169
	v_lshlrev_b32_e32 v142, 16, v224
	v_and_b32_e32 v143, 0xffff0000, v224
	v_pk_mul_f32 v[144:145], v[144:145], v[142:143]
	v_lshlrev_b32_e32 v142, 16, v225
	v_and_b32_e32 v143, 0xffff0000, v225
	v_pk_mul_f32 v[168:169], v[168:169], v[142:143]
	v_pk_mul_f32 v[82:83], v[82:83], v[144:145]
	v_pk_mul_f32 v[84:85], v[84:85], v[168:169]
	s_add_u32 s62, s40, 0x3d8b00
	s_addc_u32 s63, s41, 0
	global_load_dwordx4 v[222:225], v161, s[62:63] offset:-2048
	global_load_dwordx4 v[226:229], v161, s[62:63] offset:2048
	s_waitcnt vmcnt(14)
	v_lshlrev_b32_e32 v144, 16, v234
	v_and_b32_e32 v145, 0xffff0000, v234
	v_lshlrev_b32_e32 v168, 16, v235
	v_and_b32_e32 v169, 0xffff0000, v235
	v_rcp_f32_e32 v144, v144
	v_rcp_f32_e32 v145, v145
	v_rcp_f32_e32 v168, v168
	v_rcp_f32_e32 v169, v169
	v_lshlrev_b32_e32 v142, 16, v230
	v_and_b32_e32 v143, 0xffff0000, v230
	v_pk_mul_f32 v[144:145], v[144:145], v[142:143]
	v_lshlrev_b32_e32 v142, 16, v231
	v_and_b32_e32 v143, 0xffff0000, v231
	v_pk_mul_f32 v[168:169], v[168:169], v[142:143]
	v_pk_mul_f32 v[78:79], v[78:79], v[144:145]
	v_pk_mul_f32 v[80:81], v[80:81], v[168:169]
	v_lshlrev_b32_e32 v144, 16, v236
	v_and_b32_e32 v145, 0xffff0000, v236
	v_lshlrev_b32_e32 v168, 16, v237
	v_and_b32_e32 v169, 0xffff0000, v237
	v_rcp_f32_e32 v144, v144
	v_rcp_f32_e32 v145, v145
	v_rcp_f32_e32 v168, v168
	v_rcp_f32_e32 v169, v169
	v_lshlrev_b32_e32 v142, 16, v232
	v_and_b32_e32 v143, 0xffff0000, v232
	v_pk_mul_f32 v[144:145], v[144:145], v[142:143]
	v_lshlrev_b32_e32 v142, 16, v233
	v_and_b32_e32 v143, 0xffff0000, v233
	v_pk_mul_f32 v[168:169], v[168:169], v[142:143]
	v_pk_mul_f32 v[74:75], v[74:75], v[144:145]
	v_pk_mul_f32 v[76:77], v[76:77], v[168:169]
	s_add_u32 s62, s40, 0x43aa00
	s_addc_u32 s63, s41, 0
	global_load_dwordx4 v[230:233], v161, s[62:63] offset:-2048
	global_load_dwordx4 v[234:237], v161, s[62:63] offset:2048
	s_waitcnt vmcnt(14)
; __device__ __forceinline__ float bflo(unsigned w) { return __uint_as_float(w << 16); }
; __device__ __forceinline__ float bfhi(unsigned w) { return __uint_as_float(w & 0xffff0000u); }
;     __device__ __forceinline__ void mid(f32x4 (&acc)[2][2][4][2], const Unit& u, int wr, int wc, int fr, int fq) const {
;         int row0 = u.pm * BM + wr * 64 + fr, col0 = u.pn * BM + wc * 32 + 8 * fq;
;         asm volatile("" : "+v"(row0), "+v"(col0));
; #pragma unroll
;         for (int ai = 0; ai < 2; ++ai)
; #pragma unroll
;             for (int m = 0; m < 4; ++m) { const size_t row = (size_t)(row0 + ai * HALF + m * 16);
; #pragma unroll
;                 for (int bj = 0; bj < 2; ++bj) { const int col = col0 + bj * HALF;
;                     const u32x4 ga = *(const u32x4*)(P + row * LDP + PC_GA + col), gb = *(const u32x4*)(P + row * LDP + PC_GB + col);
; #pragma unroll
;                     for (int j = 0; j < 2; ++j) {
;                         acc[ai][bj][m][0][2 * j] *= bflo(ga[j]) * __builtin_amdgcn_rcpf(bflo(gb[j])); acc[ai][bj][m][0][2 * j + 1] *= bfhi(ga[j]) * __builtin_amdgcn_rcpf(bfhi(gb[j]));
;                         acc[ai][bj][m][1][2 * j] *= bflo(ga[2 + j]) * __builtin_amdgcn_rcpf(bflo(gb[2 + j])); acc[ai][bj][m][1][2 * j + 1] *= bfhi(ga[2 + j]) * __builtin_amdgcn_rcpf(bfhi(gb[2 + j])); } }
;                 asm volatile("" ::: "memory"); }
	v_lshlrev_b32_e32 v144, 16, v242
	v_and_b32_e32 v145, 0xffff0000, v242
	v_lshlrev_b32_e32 v168, 16, v243
	v_and_b32_e32 v169, 0xffff0000, v243
	v_rcp_f32_e32 v144, v144
	v_rcp_f32_e32 v145, v145
	v_rcp_f32_e32 v168, v168
	v_rcp_f32_e32 v169, v169
	v_lshlrev_b32_e32 v142, 16, v238
	v_and_b32_e32 v143, 0xffff0000, v238
	v_pk_mul_f32 v[144:145], v[144:145], v[142:143]
	v_lshlrev_b32_e32 v142, 16, v239
	v_and_b32_e32 v143, 0xffff0000, v239
	v_pk_mul_f32 v[168:169], v[168:169], v[142:143]
	v_pk_mul_f32 v[70:71], v[70:71], v[144:145]
	v_pk_mul_f32 v[72:73], v[72:73], v[168:169]
	v_lshlrev_b32_e32 v144, 16, v244
	v_and_b32_e32 v145, 0xffff0000, v244
	v_lshlrev_b32_e32 v168, 16, v245
	v_and_b32_e32 v169, 0xffff0000, v245
	v_rcp_f32_e32 v144, v144
	v_rcp_f32_e32 v145, v145
	v_rcp_f32_e32 v168, v168
	v_rcp_f32_e32 v169, v169
	v_lshlrev_b32_e32 v142, 16, v240
	v_and_b32_e32 v143, 0xffff0000, v240
	v_pk_mul_f32 v[144:145], v[144:145], v[142:143]
	v_lshlrev_b32_e32 v142, 16, v241
	v_and_b32_e32 v143, 0xffff0000, v241
	v_pk_mul_f32 v[168:169], v[168:169], v[142:143]
	v_pk_mul_f32 v[66:67], v[66:67], v[144:145]
	v_pk_mul_f32 v[68:69], v[68:69], v[168:169]
	s_add_u32 s62, s40, 0x43ab00
	s_addc_u32 s63, s41, 0
	global_load_dwordx4 v[238:241], v161, s[62:63] offset:-2048
	global_load_dwordx4 v[242:245], v161, s[62:63] offset:2048
	s_waitcnt vmcnt(14)
	v_lshlrev_b32_e32 v144, 16, v134
	v_and_b32_e32 v145, 0xffff0000, v134
	v_lshlrev_b32_e32 v168, 16, v135
	v_and_b32_e32 v169, 0xffff0000, v135
	v_rcp_f32_e32 v144, v144
	v_rcp_f32_e32 v145, v145
	v_rcp_f32_e32 v168, v168
	v_rcp_f32_e32 v169, v169
	v_lshlrev_b32_e32 v142, 16, v130
	v_and_b32_e32 v143, 0xffff0000, v130
	v_pk_mul_f32 v[144:145], v[144:145], v[142:143]
	v_lshlrev_b32_e32 v142, 16, v131
	v_and_b32_e32 v143, 0xffff0000, v131
	v_pk_mul_f32 v[168:169], v[168:169], v[142:143]
	v_pk_mul_f32 v[62:63], v[62:63], v[144:145]
	v_pk_mul_f32 v[64:65], v[64:65], v[168:169]
	v_lshlrev_b32_e32 v144, 16, v136
	v_and_b32_e32 v145, 0xffff0000, v136
	v_lshlrev_b32_e32 v168, 16, v137
	v_and_b32_e32 v169, 0xffff0000, v137
	v_rcp_f32_e32 v144, v144
	v_rcp_f32_e32 v145, v145
	v_rcp_f32_e32 v168, v168
	v_rcp_f32_e32 v169, v169
	v_lshlrev_b32_e32 v142, 16, v132
	v_and_b32_e32 v143, 0xffff0000, v132
	v_pk_mul_f32 v[144:145], v[144:145], v[142:143]
	v_lshlrev_b32_e32 v142, 16, v133
	v_and_b32_e32 v143, 0xffff0000, v133
	v_pk_mul_f32 v[168:169], v[168:169], v[142:143]
	v_pk_mul_f32 v[58:59], v[58:59], v[144:145]
	v_pk_mul_f32 v[60:61], v[60:61], v[168:169]
	s_waitcnt vmcnt(12)
	v_lshlrev_b32_e32 v144, 16, v190
	v_and_b32_e32 v145, 0xffff0000, v190
	v_lshlrev_b32_e32 v168, 16, v191
	v_and_b32_e32 v169, 0xffff0000, v191
	v_rcp_f32_e32 v144, v144
	v_rcp_f32_e32 v145, v145
	v_rcp_f32_e32 v168, v168
	v_rcp_f32_e32 v169, v169
	v_lshlrev_b32_e32 v142, 16, v186
	v_and_b32_e32 v143, 0xffff0000, v186
	v_pk_mul_f32 v[144:145], v[144:145], v[142:143]
	v_lshlrev_b32_e32 v142, 16, v187
	v_and_b32_e32 v143, 0xffff0000, v187
	v_pk_mul_f32 v[168:169], v[168:169], v[142:143]
	v_pk_mul_f32 v[54:55], v[54:55], v[144:145]
	v_pk_mul_f32 v[56:57], v[56:57], v[168:169]
	v_lshlrev_b32_e32 v144, 16, v192
	v_and_b32_e32 v145, 0xffff0000, v192
	v_lshlrev_b32_e32 v168, 16, v193
	v_and_b32_e32 v169, 0xffff0000, v193
	v_rcp_f32_e32 v144, v144
	v_rcp_f32_e32 v145, v145
	v_rcp_f32_e32 v168, v168
	v_rcp_f32_e32 v169, v169
	v_lshlrev_b32_e32 v142, 16, v188
	v_and_b32_e32 v143, 0xffff0000, v188
	v_pk_mul_f32 v[144:145], v[144:145], v[142:143]
	v_lshlrev_b32_e32 v142, 16, v189
	v_and_b32_e32 v143, 0xffff0000, v189
	v_pk_mul_f32 v[168:169], v[168:169], v[142:143]
	v_pk_mul_f32 v[50:51], v[50:51], v[144:145]
	v_pk_mul_f32 v[52:53], v[52:53], v[168:169]
	s_waitcnt vmcnt(10)
	v_lshlrev_b32_e32 v144, 16, v198
	v_and_b32_e32 v145, 0xffff0000, v198
	v_lshlrev_b32_e32 v168, 16, v199
	v_and_b32_e32 v169, 0xffff0000, v199
	v_rcp_f32_e32 v144, v144
	v_rcp_f32_e32 v145, v145
	v_rcp_f32_e32 v168, v168
	v_rcp_f32_e32 v169, v169
	v_lshlrev_b32_e32 v142, 16, v194
	v_and_b32_e32 v143, 0xffff0000, v194
	v_pk_mul_f32 v[144:145], v[144:145], v[142:143]
	v_lshlrev_b32_e32 v142, 16, v195
	v_and_b32_e32 v143, 0xffff0000, v195
	v_pk_mul_f32 v[168:169], v[168:169], v[142:143]
	v_pk_mul_f32 v[46:47], v[46:47], v[144:145]
	v_pk_mul_f32 v[48:49], v[48:49], v[168:169]
	v_lshlrev_b32_e32 v144, 16, v200
	v_and_b32_e32 v145, 0xffff0000, v200
	v_lshlrev_b32_e32 v168, 16, v201
	v_and_b32_e32 v169, 0xffff0000, v201
	v_rcp_f32_e32 v144, v144
	v_rcp_f32_e32 v145, v145
	v_rcp_f32_e32 v168, v168
	v_rcp_f32_e32 v169, v169
	v_lshlrev_b32_e32 v142, 16, v196
	v_and_b32_e32 v143, 0xffff0000, v196
	v_pk_mul_f32 v[144:145], v[144:145], v[142:143]
	v_lshlrev_b32_e32 v142, 16, v197
	v_and_b32_e32 v143, 0xffff0000, v197
	v_pk_mul_f32 v[168:169], v[168:169], v[142:143]
	v_pk_mul_f32 v[42:43], v[42:43], v[144:145]
	v_pk_mul_f32 v[44:45], v[44:45], v[168:169]
	s_waitcnt vmcnt(8)
; __device__ __forceinline__ float bflo(unsigned w) { return __uint_as_float(w << 16); }
; __device__ __forceinline__ float bfhi(unsigned w) { return __uint_as_float(w & 0xffff0000u); }
;     __device__ __forceinline__ void mid(f32x4 (&acc)[2][2][4][2], const Unit& u, int wr, int wc, int fr, int fq) const {
;         int row0 = u.pm * BM + wr * 64 + fr, col0 = u.pn * BM + wc * 32 + 8 * fq;
;         asm volatile("" : "+v"(row0), "+v"(col0));
; #pragma unroll
;         for (int ai = 0; ai < 2; ++ai)
; #pragma unroll
;             for (int m = 0; m < 4; ++m) { const size_t row = (size_t)(row0 + ai * HALF + m * 16);
; #pragma unroll
;                 for (int bj = 0; bj < 2; ++bj) { const int col = col0 + bj * HALF;
;                     const u32x4 ga = *(const u32x4*)(P + row * LDP + PC_GA + col), gb = *(const u32x4*)(P + row * LDP + PC_GB + col);
; #pragma unroll
;                     for (int j = 0; j < 2; ++j) {
;                         acc[ai][bj][m][0][2 * j] *= bflo(ga[j]) * __builtin_amdgcn_rcpf(bflo(gb[j])); acc[ai][bj][m][0][2 * j + 1] *= bfhi(ga[j]) * __builtin_amdgcn_rcpf(bfhi(gb[j]));
;                         acc[ai][bj][m][1][2 * j] *= bflo(ga[2 + j]) * __builtin_amdgcn_rcpf(bflo(gb[2 + j])); acc[ai][bj][m][1][2 * j + 1] *= bfhi(ga[2 + j]) * __builtin_amdgcn_rcpf(bfhi(gb[2 + j])); } }
;                 asm volatile("" ::: "memory"); }
; template <class Epi, class Sched, bool ALIGN_EPI = false, bool SP2 = false>
; __device__ __forceinline__ void gemm_phase(PG8_LAS unsigned char* lds, const Gemm g, const Sched& S, const Epi& E) {
;     ...
;             if constexpr (Epi::MID) { if (t == nt / 2) E.mid(acc, cur, wr, wc, fr, fq); }
	v_lshlrev_b32_e32 v144, 16, v206
	v_and_b32_e32 v145, 0xffff0000, v206
	v_lshlrev_b32_e32 v168, 16, v207
	v_and_b32_e32 v169, 0xffff0000, v207
	v_rcp_f32_e32 v144, v144
	v_rcp_f32_e32 v145, v145
	v_rcp_f32_e32 v168, v168
	v_rcp_f32_e32 v169, v169
	v_lshlrev_b32_e32 v142, 16, v202
	v_and_b32_e32 v143, 0xffff0000, v202
	v_pk_mul_f32 v[144:145], v[144:145], v[142:143]
	v_lshlrev_b32_e32 v142, 16, v203
	v_and_b32_e32 v143, 0xffff0000, v203
	v_pk_mul_f32 v[168:169], v[168:169], v[142:143]
	v_pk_mul_f32 v[38:39], v[38:39], v[144:145]
	v_pk_mul_f32 v[40:41], v[40:41], v[168:169]
	v_lshlrev_b32_e32 v144, 16, v208
	v_and_b32_e32 v145, 0xffff0000, v208
	v_lshlrev_b32_e32 v168, 16, v209
	v_and_b32_e32 v169, 0xffff0000, v209
	v_rcp_f32_e32 v144, v144
	v_rcp_f32_e32 v145, v145
	v_rcp_f32_e32 v168, v168
	v_rcp_f32_e32 v169, v169
	v_lshlrev_b32_e32 v142, 16, v204
	v_and_b32_e32 v143, 0xffff0000, v204
	v_pk_mul_f32 v[144:145], v[144:145], v[142:143]
	v_lshlrev_b32_e32 v142, 16, v205
	v_and_b32_e32 v143, 0xffff0000, v205
	v_pk_mul_f32 v[168:169], v[168:169], v[142:143]
	v_pk_mul_f32 v[34:35], v[34:35], v[144:145]
	v_pk_mul_f32 v[36:37], v[36:37], v[168:169]
	s_waitcnt vmcnt(6)
	v_lshlrev_b32_e32 v144, 16, v218
	v_and_b32_e32 v145, 0xffff0000, v218
	v_lshlrev_b32_e32 v168, 16, v219
	v_and_b32_e32 v169, 0xffff0000, v219
	v_rcp_f32_e32 v144, v144
	v_rcp_f32_e32 v145, v145
	v_rcp_f32_e32 v168, v168
	v_rcp_f32_e32 v169, v169
	v_lshlrev_b32_e32 v142, 16, v214
	v_and_b32_e32 v143, 0xffff0000, v214
	v_pk_mul_f32 v[144:145], v[144:145], v[142:143]
	v_lshlrev_b32_e32 v142, 16, v215
	v_and_b32_e32 v143, 0xffff0000, v215
	v_pk_mul_f32 v[168:169], v[168:169], v[142:143]
	v_pk_mul_f32 v[30:31], v[30:31], v[144:145]
	v_pk_mul_f32 v[32:33], v[32:33], v[168:169]
	v_lshlrev_b32_e32 v144, 16, v220
	v_and_b32_e32 v145, 0xffff0000, v220
	v_lshlrev_b32_e32 v168, 16, v221
	v_and_b32_e32 v169, 0xffff0000, v221
	v_rcp_f32_e32 v144, v144
	v_rcp_f32_e32 v145, v145
	v_rcp_f32_e32 v168, v168
	v_rcp_f32_e32 v169, v169
	v_lshlrev_b32_e32 v142, 16, v216
	v_and_b32_e32 v143, 0xffff0000, v216
	v_pk_mul_f32 v[144:145], v[144:145], v[142:143]
	v_lshlrev_b32_e32 v142, 16, v217
	v_and_b32_e32 v143, 0xffff0000, v217
	v_pk_mul_f32 v[168:169], v[168:169], v[142:143]
	v_pk_mul_f32 v[26:27], v[26:27], v[144:145]
	v_pk_mul_f32 v[28:29], v[28:29], v[168:169]
	s_waitcnt vmcnt(4)
	v_lshlrev_b32_e32 v144, 16, v226
	v_and_b32_e32 v145, 0xffff0000, v226
	v_lshlrev_b32_e32 v168, 16, v227
	v_and_b32_e32 v169, 0xffff0000, v227
	v_rcp_f32_e32 v144, v144
	v_rcp_f32_e32 v145, v145
	v_rcp_f32_e32 v168, v168
	v_rcp_f32_e32 v169, v169
	v_lshlrev_b32_e32 v142, 16, v222
	v_and_b32_e32 v143, 0xffff0000, v222
	v_pk_mul_f32 v[144:145], v[144:145], v[142:143]
	v_lshlrev_b32_e32 v142, 16, v223
	v_and_b32_e32 v143, 0xffff0000, v223
	v_pk_mul_f32 v[168:169], v[168:169], v[142:143]
	v_pk_mul_f32 v[22:23], v[22:23], v[144:145]
	v_pk_mul_f32 v[24:25], v[24:25], v[168:169]
	v_lshlrev_b32_e32 v144, 16, v228
	v_and_b32_e32 v145, 0xffff0000, v228
	v_lshlrev_b32_e32 v168, 16, v229
	v_and_b32_e32 v169, 0xffff0000, v229
	v_rcp_f32_e32 v144, v144
	v_rcp_f32_e32 v145, v145
	v_rcp_f32_e32 v168, v168
	v_rcp_f32_e32 v169, v169
	v_lshlrev_b32_e32 v142, 16, v224
	v_and_b32_e32 v143, 0xffff0000, v224
	v_pk_mul_f32 v[144:145], v[144:145], v[142:143]
	v_lshlrev_b32_e32 v142, 16, v225
	v_and_b32_e32 v143, 0xffff0000, v225
	v_pk_mul_f32 v[168:169], v[168:169], v[142:143]
	v_pk_mul_f32 v[18:19], v[18:19], v[144:145]
	v_pk_mul_f32 v[20:21], v[20:21], v[168:169]
	s_waitcnt vmcnt(2)
	v_lshlrev_b32_e32 v144, 16, v234
	v_and_b32_e32 v145, 0xffff0000, v234
	v_lshlrev_b32_e32 v168, 16, v235
	v_and_b32_e32 v169, 0xffff0000, v235
	v_rcp_f32_e32 v144, v144
	v_rcp_f32_e32 v145, v145
	v_rcp_f32_e32 v168, v168
	v_rcp_f32_e32 v169, v169
	v_lshlrev_b32_e32 v142, 16, v230
	v_and_b32_e32 v143, 0xffff0000, v230
	v_pk_mul_f32 v[144:145], v[144:145], v[142:143]
	v_lshlrev_b32_e32 v142, 16, v231
	v_and_b32_e32 v143, 0xffff0000, v231
	v_pk_mul_f32 v[168:169], v[168:169], v[142:143]
	v_pk_mul_f32 v[14:15], v[14:15], v[144:145]
	v_pk_mul_f32 v[16:17], v[16:17], v[168:169]
	v_lshlrev_b32_e32 v144, 16, v236
	v_and_b32_e32 v145, 0xffff0000, v236
	v_lshlrev_b32_e32 v168, 16, v237
	v_and_b32_e32 v169, 0xffff0000, v237
	v_rcp_f32_e32 v144, v144
	v_rcp_f32_e32 v145, v145
	v_rcp_f32_e32 v168, v168
	v_rcp_f32_e32 v169, v169
	v_lshlrev_b32_e32 v142, 16, v232
	v_and_b32_e32 v143, 0xffff0000, v232
	v_pk_mul_f32 v[144:145], v[144:145], v[142:143]
	v_lshlrev_b32_e32 v142, 16, v233
	v_and_b32_e32 v143, 0xffff0000, v233
	v_pk_mul_f32 v[168:169], v[168:169], v[142:143]
	v_pk_mul_f32 v[10:11], v[10:11], v[144:145]
	v_pk_mul_f32 v[12:13], v[12:13], v[168:169]
	s_waitcnt vmcnt(0)
	v_lshlrev_b32_e32 v144, 16, v242
	v_and_b32_e32 v145, 0xffff0000, v242
	v_lshlrev_b32_e32 v168, 16, v243
	v_and_b32_e32 v169, 0xffff0000, v243
	v_rcp_f32_e32 v144, v144
	v_rcp_f32_e32 v145, v145
	v_rcp_f32_e32 v168, v168
	v_rcp_f32_e32 v169, v169
	v_lshlrev_b32_e32 v142, 16, v238
	v_and_b32_e32 v143, 0xffff0000, v238
	v_pk_mul_f32 v[144:145], v[144:145], v[142:143]
	v_lshlrev_b32_e32 v142, 16, v239
	v_and_b32_e32 v143, 0xffff0000, v239
	v_pk_mul_f32 v[168:169], v[168:169], v[142:143]
	v_pk_mul_f32 v[6:7], v[6:7], v[144:145]
	v_pk_mul_f32 v[8:9], v[8:9], v[168:169]
	v_lshlrev_b32_e32 v144, 16, v244
	v_and_b32_e32 v145, 0xffff0000, v244
	v_lshlrev_b32_e32 v168, 16, v245
	v_and_b32_e32 v169, 0xffff0000, v245
	v_rcp_f32_e32 v144, v144
	v_rcp_f32_e32 v145, v145
	v_rcp_f32_e32 v168, v168
	v_rcp_f32_e32 v169, v169
	v_lshlrev_b32_e32 v142, 16, v240
	v_and_b32_e32 v143, 0xffff0000, v240
	v_pk_mul_f32 v[144:145], v[144:145], v[142:143]
	v_lshlrev_b32_e32 v142, 16, v241
	v_and_b32_e32 v143, 0xffff0000, v241
	v_pk_mul_f32 v[168:169], v[168:169], v[142:143]
	v_pk_mul_f32 v[2:3], v[2:3], v[144:145]
	v_pk_mul_f32 v[4:5], v[4:5], v[168:169]
	s_branch .LBB0_77
